# w_out_ab conversion moved out of P0 into the ATT-end barrier wait of the prompt-attention workgroups (waves 1..7, 1-2 items each, registers saved around hipcc's loop)
# speedup vs baseline: 1.0819x; 1.0081x over previous
.LBB0_10:
	s_cmp_lg_u32 s98, 0
	s_cbranch_scc1 .Lp0_noskip
	s_cmp_lg_u32 s97, 0x100
	s_cbranch_scc1 .Lp0_noskip
	s_add_i32 s0, s44, 0xffffe000
	s_cmp_lt_u32 s0, 0x800
	s_cbranch_scc1 .LBB0_9

.Ltr_b2:
	s_cmp_eq_u32 s98, 3
	s_cbranch_scc1 .Lb3_ret
	s_branch .Ltr_b3

.LBB0_916:
	s_waitcnt vmcnt(0)
	s_barrier
	s_cmp_eq_u32 s97, 0x100
	s_cbranch_scc0 .Lb3_skip
	v_readlane_b32 s7, v255, 2
	v_readlane_b32 s6, v255, 7
	s_nop 0
	s_lshr_b32 s7, s7, 6
	s_cmp_eq_u32 s7, 0
	s_cbranch_scc1 .Lb3_skip
	s_and_b32 s48, s6, 31
	s_cmp_gt_u32 s48, 19
	s_cbranch_scc1 .Lb3_skip
	v_writelane_b32 v138, s14, 0
	v_writelane_b32 v138, s15, 1
	v_writelane_b32 v138, s30, 2
	v_writelane_b32 v138, s34, 3
	v_writelane_b32 v138, s92, 4
	v_writelane_b32 v138, exec_lo, 5
	v_writelane_b32 v138, exec_hi, 6
	v_writelane_b32 v138, s46, 7
	v_writelane_b32 v138, s47, 8
	s_mov_b64 exec, -1
	v_mov_b32_e32 v106, v1
	v_mov_b32_e32 v107, v4
	v_mov_b32_e32 v108, v5
	v_mov_b32_e32 v109, v6
	v_mov_b32_e32 v110, v7
	v_mov_b32_e32 v111, v8
	v_mov_b32_e32 v112, v9
	v_mov_b32_e32 v113, v10
	v_mov_b32_e32 v114, v11
	v_mov_b32_e32 v115, v12
	v_mov_b32_e32 v116, v13
	v_mov_b32_e32 v117, v14
	v_mov_b32_e32 v118, v15
	v_mov_b32_e32 v119, v16
	v_mov_b32_e32 v120, v17
	v_mov_b32_e32 v121, v21
	v_mov_b32_e32 v122, v24
	v_mov_b32_e32 v123, v25
	v_mov_b32_e32 v124, v26
	v_mov_b32_e32 v125, v27
	v_mov_b32_e32 v126, v30
	v_mov_b32_e32 v127, v31
	v_mov_b32_e32 v128, v34
	v_mov_b32_e32 v129, v35
	v_mov_b32_e32 v130, v47
	v_mov_b32_e32 v131, v48
	v_mov_b32_e32 v132, v49
	v_mov_b32_e32 v133, v73
	v_mov_b32_e32 v134, v86
	v_mov_b32_e32 v135, v87
	v_mov_b32_e32 v136, v104
	v_mov_b32_e32 v137, v105
	s_lshr_b32 s92, s6, 5
	s_mul_i32 s92, s92, 20
	s_add_i32 s92, s92, s48
	s_mul_i32 s92, s92, 7
	s_add_i32 s92, s92, s7
	s_add_i32 s92, s92, 0x1fff
	s_mov_b64 s[100:101], s[4:5]
	s_mov_b32 s98, 3
	s_mov_b32 s99, 0x27ff
	s_movk_i32 s48, 0x460
	v_readlane_b32 s0, v255, 3
	v_readlane_b32 s1, v255, 4
	v_readlane_b32 s2, v255, 0
	v_readlane_b32 s3, v255, 1
	v_mov_b32_e32 v163, v0
	v_and_b32_e32 v162, 63, v0
	s_lshl_b32 s30, s7, 14
	s_nop 4
	s_branch .Ltr_f2
.Lb3_ret:
	s_mov_b32 s98, 0
	s_mov_b64 s[4:5], s[100:101]
	s_mov_b64 exec, -1
	v_mov_b32_e32 v1, v106
	v_mov_b32_e32 v4, v107
	v_mov_b32_e32 v5, v108
	v_mov_b32_e32 v6, v109
	v_mov_b32_e32 v7, v110
	v_mov_b32_e32 v8, v111
	v_mov_b32_e32 v9, v112
	v_mov_b32_e32 v10, v113
	v_mov_b32_e32 v11, v114
	v_mov_b32_e32 v12, v115
	v_mov_b32_e32 v13, v116
	v_mov_b32_e32 v14, v117
	v_mov_b32_e32 v15, v118
	v_mov_b32_e32 v16, v119
	v_mov_b32_e32 v17, v120
	v_mov_b32_e32 v21, v121
	v_mov_b32_e32 v24, v122
	v_mov_b32_e32 v25, v123
	v_mov_b32_e32 v26, v124
	v_mov_b32_e32 v27, v125
	v_mov_b32_e32 v30, v126
	v_mov_b32_e32 v31, v127
	v_mov_b32_e32 v34, v128
	v_mov_b32_e32 v35, v129
	v_mov_b32_e32 v47, v130
	v_mov_b32_e32 v48, v131
	v_mov_b32_e32 v49, v132
	v_mov_b32_e32 v73, v133
	v_mov_b32_e32 v86, v134
	v_mov_b32_e32 v87, v135
	v_mov_b32_e32 v104, v136
	v_mov_b32_e32 v105, v137
	v_readlane_b32 s14, v138, 0
	v_readlane_b32 s15, v138, 1
	v_readlane_b32 s30, v138, 2
	v_readlane_b32 s34, v138, 3
	v_readlane_b32 s92, v138, 4
	v_readlane_b32 s6, v138, 5
	v_readlane_b32 s7, v138, 6
	v_readlane_b32 s46, v138, 7
	v_readlane_b32 s47, v138, 8
	s_nop 1
	s_mov_b64 exec, s[6:7]
.Lb3_skip:
	s_mov_b64 s[2:3], exec
	v_readlane_b32 s0, v255, 11
	v_readlane_b32 s1, v255, 12
	s_and_b64 s[0:1], s[2:3], s[0:1]
	s_mov_b64 exec, s[0:1]
	s_cbranch_execz .LBB0_968
	s_add_i32 s0, 0, 0x20000
	v_mov_b32_e32 v2, s0
	s_waitcnt vmcnt(0) expcnt(0) lgkmcnt(0)
	ds_read_b32 v4, v2
	s_add_i32 s0, 0, 0x20004
	v_mov_b32_e32 v2, s0
	ds_read_b32 v2, v2
	s_waitcnt lgkmcnt(1)
	v_cmp_ne_u32_e32 vcc, 0, v4
	s_cbranch_vccnz .LBB0_932
	v_readlane_b32 s0, v255, 5
	v_readlane_b32 s1, v255, 6
	s_load_dwordx2 s[6:7], s[0:1], 0x4
	v_readlane_b32 s36, v255, 0
	v_readlane_b32 s37, v255, 1
	s_add_u32 s0, s36, 0x5e0200
	s_addc_u32 s1, s37, 0
	s_add_u32 s4, s36, 0x5e0400
	s_addc_u32 s5, s37, 0
	s_waitcnt lgkmcnt(0)
	s_mul_i32 s33, s6, s97
	s_add_u32 s6, s36, 0x5e0500
	s_mul_i32 s33, s33, s7
	s_addc_u32 s7, s37, 0
	s_add_u32 s8, s36, 0x5e0600
	s_addc_u32 s9, s37, 0
	s_add_u32 s10, s36, 0x5e0700
	s_addc_u32 s11, s37, 0
	s_add_u32 s12, s36, 0x5e0800
	s_addc_u32 s13, s37, 0
	s_add_u32 s14, s36, 0x5e0900
	s_addc_u32 s15, s37, 0
	s_add_u32 s16, s36, 0x5e0a00
	s_addc_u32 s17, s37, 0
	s_add_u32 s18, s36, 0x5e0b00
	s_addc_u32 s19, s37, 0
	s_add_u32 s20, s36, 0x5e0c00
	s_addc_u32 s21, s37, 0
	s_add_u32 s22, s36, 0x5e0d00
	s_addc_u32 s23, s37, 0
	s_add_u32 s24, s36, 0x5e0e00
	s_addc_u32 s25, s37, 0
	s_add_u32 s26, s36, 0x5e0f00
	s_addc_u32 s27, s37, 0
	s_add_u32 s28, s36, 0x5e1000
	s_addc_u32 s29, s37, 0
	s_add_u32 s30, s36, 0x5e1100
	s_addc_u32 s31, s37, 0
	s_add_u32 s34, s36, 0x5e1200
	s_addc_u32 s35, s37, 0
	s_add_u32 s36, s36, 0x5e1300
	s_addc_u32 s37, s37, 0
	s_mov_b32 s44, 1
	v_mov_b32_e32 v18, 0
	s_branch .LBB0_920
